# bias table staged in LDS (no vmcnt(0) in attention loop), scalar-controlled top-k bisection with pair-max step skipping, double-buffered QK K-fragment reads
# speedup vs baseline: 1.1057x; 1.0218x over previous
; __device__ __forceinline__ void attn_item(const Ptrs& P, unsigned char* lds, int b, int tq0, int tid) {
;     const int lane = tid & 63, w = __builtin_amdgcn_readfirstlane(tid >> 6), g = lane >> 4, r16 = lane & 15;
;     constexpr int SP = 264;
;     bf16_t* stg = (bf16_t*)lds;
;     unsigned char* l2 = lds + 135168;
;     unsigned short* sel = (unsigned short*)l2;
;     unsigned* cntw = (unsigned*)(l2 + 2048);
;     unsigned* gte = (unsigned*)(l2 + 2048 + 256);
;     bf16_t* Pm = (bf16_t*)(l2 + 4096);
;     ...
;             int dist = tq - idx; dist = dist > 128 ? 128 : dist; dist = dist < 0 ? 0 : dist;
;             const f32x4 bb = *(const f32x4*)(P.BT + dist * 16 + 4 * g);
.LBB0_462:
	s_or_b64 exec, exec, s[0:1]
	v_lshlrev_b32_e32 v2, 2, v188
	v_and_b32_e32 v4, 12, v2
	v_lshlrev_b32_e32 v2, 3, v188
	v_and_b32_e32 v194, 15, v188
	v_mov_b32_e32 v165, 0
	v_and_b32_e32 v196, 0xf8, v2
	v_lshlrev_b32_e32 v164, 7, v194
	v_lshlrev_b32_e32 v2, 1, v196
	v_mov_b32_e32 v3, v165
	v_lshl_add_u64 v[0:1], s[74:75], 0, v[164:165]
	v_and_b32_e32 v164, 48, v188
	v_lshl_add_u64 v[2:3], s[56:57], 0, v[2:3]
	s_mov_b64 s[12:13], 0x16000000
	v_lshlrev_b32_e32 v166, 3, v90
	v_lshl_add_u64 v[168:169], v[0:1], 0, v[164:165]
	v_bfe_u32 v1, v188, 2, 2
	v_lshl_add_u64 v[174:175], v[2:3], 0, s[12:13]
	v_lshrrev_b32_e32 v2, 5, v188
	v_or_b32_e32 v198, 30, v2
	v_lshl_add_u64 v[2:3], s[56:57], 0, v[164:165]
	s_mov_b64 s[12:13], 0x100000
	v_or_b32_e32 v1, v166, v1
	v_add_u32_e32 v176, 0x25000, v164
	v_mul_u32_u24_e32 v1, 0x108, v1
	s_movk_i32 s12, 0x200
	v_add_lshl_u32 v205, v1, v4, 1
	v_sub_u32_e64 v1, s12, v188 clamp
	v_add_u32_e32 v1, 0x1ff, v1
	v_lshrrev_b32_e32 v178, 9, v1
	v_add_u32_e32 v1, 2, v178
	v_and_b32_e32 v207, 6, v1
	v_lshrrev_b32_e32 v1, 8, v188
	v_or_b32_e32 v208, 0x1ffc, v1
	v_lshl_add_u32 v1, v188, 1, 0
	v_add_u32_e32 v209, 0x21000, v1
	v_add_u32_e32 v1, 0x200, v188
	v_lshrrev_b32_e32 v1, 8, v1
	s_mov_b32 s22, 0
	s_lshr_b32 s3, s2, 1
	v_and_b32_e32 v179, 63, v188
	v_lshlrev_b32_e32 v0, 8, v194
	v_bfe_u32 v197, v188, 5, 1
	v_mul_u32_u24_e32 v5, 0xa0, v90
	v_add_u32_e32 v210, 0x1ffc, v1
	v_lshl_add_u32 v1, v198, 1, 0
	s_mov_b64 s[20:21], src_shared_base
	s_mov_b32 s23, 1
	v_cmp_eq_u32_e64 s[0:1], 0, v188
	v_lshl_add_u64 v[170:171], s[78:79], 0, v[164:165]
	v_lshlrev_b32_e32 v2, 4, v179
	v_mov_b32_e32 v3, 0
	v_lshl_add_u64 v[172:173], s[50:51], 0, v[2:3]
	v_cmp_eq_u32_e64 s[4:5], 0, v179
	v_cmp_gt_u32_e64 s[6:7], 16, v179
	v_cmp_lt_u32_e64 s[8:9], 31, v179
	v_cmp_eq_u32_e64 s[10:11], 48, v164
	v_and_b32_e32 v195, 0xff, v188
	v_mul_u32_u24_e32 v199, 0x50, v194
	v_mul_u32_u24_e32 v200, 0x210, v197
	v_mul_u32_u24_e32 v201, 0x210, v198
	v_mul_u32_u24_e32 v202, 0x210, v194
	v_lshl_add_u32 v203, v179, 2, 0
	v_lshl_or_b32 v204, v90, 10, v194
	v_mov_b32_e32 v167, v178
	v_add_u32_e32 v211, 0x21040, v1
	v_lshl_add_u32 v212, v194, 1, 0
	v_lshl_add_u32 v213, v197, 1, 0
	s_add_i32 s33, 0, 0x24100
	v_lshlrev_b32_e32 v180, 1, v0
	v_lshlrev_b32_e32 v214, 1, v5
	v_mov_b32_e32 v215, 0x80
	v_mov_b32_e32 v216, 0xf149f2ca
	s_mov_b32 s35, s3
	s_mov_b32 s80, s22
	s_add_u32 s16, s56, 0x100000
	s_addc_u32 s17, s57, 0
	v_lshlrev_b32_e32 v236, 4, v188
	v_add_u32_e32 v237, 0x2000, v236
	v_add_u32_e32 v238, 0x25000, v236
	global_load_dwordx4 v[240:243], v236, s[16:17]
	v_cmp_gt_u32_e32 vcc, 4, v188
	s_and_saveexec_b64 s[18:19], vcc
	s_cbranch_execz .Lbt_tail_done
	global_load_dwordx4 v[244:247], v237, s[16:17]
	s_waitcnt vmcnt(0)
	ds_write_b128 v238, v[244:247] offset:8192
.Lbt_tail_done:
	s_or_b64 exec, exec, s[18:19]
	s_waitcnt vmcnt(0)
	ds_write_b128 v238, v[240:243]
	s_nop 0
	s_nop 0
	s_nop 0
	s_nop 0
	s_nop 0
	s_nop 0
	s_nop 0
	s_nop 0
	s_nop 0
	s_nop 0
	s_waitcnt vmcnt(0) lgkmcnt(0)
	s_barrier
	s_branch .LBB0_464

; __device__ __forceinline__ void attn_item(const Ptrs& P, unsigned char* lds, int b, int tq0, int tid) {
;     ...
; #pragma unroll
;         for (int r = 0; r < 64; ++r) k2[r] = (2 * r + hs < nch) ? k2[r] : 0u;
;         const int nact = (nch + 1 - hs) >> 1;
.LBB0_489:
	s_or_b64 exec, exec, s[12:13]
	s_or_b32 s12, s64, 2
	v_cmp_le_u32_e32 vcc, s12, v125
	s_or_b32 s12, s64, 4
	s_mov_b32 s75, 31
	v_cndmask_b32_e32 v95, 0, v7, vcc
	v_cmp_le_u32_e32 vcc, s12, v125
	s_or_b32 s12, s64, 6
	s_mov_b64 s[72:73], 0
	v_cndmask_b32_e32 v94, 0, v20, vcc
	v_cmp_le_u32_e32 vcc, s12, v125
	s_or_b32 s12, s64, 8
	s_nop 0
	v_cndmask_b32_e32 v93, 0, v21, vcc
	v_cmp_le_u32_e32 vcc, s12, v125
	s_or_b32 s12, s64, 10
	s_nop 0
	v_cndmask_b32_e32 v92, 0, v18, vcc
	v_cmp_le_u32_e32 vcc, s12, v125
	s_or_b32 s12, s64, 12
	s_nop 0
	v_cndmask_b32_e32 v91, 0, v19, vcc
	v_cmp_le_u32_e32 vcc, s12, v125
	s_or_b32 s12, s64, 14
	s_nop 0
	v_cndmask_b32_e32 v90, 0, v16, vcc
	v_cmp_le_u32_e32 vcc, s12, v125
	s_or_b32 s12, s64, 16
	s_nop 0
	v_cndmask_b32_e32 v89, 0, v17, vcc
	v_cmp_le_u32_e32 vcc, s12, v125
	s_or_b32 s12, s64, 18
	s_nop 0
	v_cndmask_b32_e32 v88, 0, v14, vcc
	v_cmp_le_u32_e32 vcc, s12, v125
	s_or_b32 s12, s64, 20
	s_nop 0
	v_cndmask_b32_e32 v87, 0, v15, vcc
	v_cmp_le_u32_e32 vcc, s12, v125
	s_or_b32 s12, s64, 22
	s_nop 0
	v_cndmask_b32_e32 v86, 0, v12, vcc
	v_cmp_le_u32_e32 vcc, s12, v125
	s_or_b32 s12, s64, 24
	s_nop 0
	v_cndmask_b32_e32 v85, 0, v13, vcc
	v_cmp_le_u32_e32 vcc, s12, v125
	s_or_b32 s12, s64, 26
	s_nop 0
	v_cndmask_b32_e32 v84, 0, v10, vcc
	v_cmp_le_u32_e32 vcc, s12, v125
	s_or_b32 s12, s64, 28
	s_nop 0
	v_cndmask_b32_e32 v83, 0, v11, vcc
	v_cmp_le_u32_e32 vcc, s12, v125
	s_or_b32 s12, s64, 30
	s_nop 0
	v_cndmask_b32_e32 v82, 0, v8, vcc
	v_cmp_le_u32_e32 vcc, s12, v125
	s_or_b32 s12, s64, 34
	s_nop 0
	v_cndmask_b32_e32 v81, 0, v9, vcc
	v_cmp_le_u32_e32 vcc, s12, v125
	s_or_b32 s12, s64, 36
	s_nop 0
	v_cndmask_b32_e32 v80, 0, v5, vcc
	v_cmp_le_u32_e32 vcc, s12, v125
	s_or_b32 s12, s64, 38
	s_nop 0
	v_cndmask_b32_e32 v79, 0, v34, vcc
	v_cmp_le_u32_e32 vcc, s12, v125
	s_or_b32 s12, s64, 40
	s_nop 0
	v_cndmask_b32_e32 v78, 0, v35, vcc
	v_cmp_le_u32_e32 vcc, s12, v125
	s_or_b32 s12, s64, 42
	s_nop 0
	v_cndmask_b32_e32 v77, 0, v32, vcc
	v_cmp_le_u32_e32 vcc, s12, v125
	s_or_b32 s12, s64, 44
	s_nop 0
	v_cndmask_b32_e32 v76, 0, v33, vcc
	v_cmp_le_u32_e32 vcc, s12, v125
	s_or_b32 s12, s64, 46
	s_nop 0
	v_cndmask_b32_e32 v75, 0, v30, vcc
	v_cmp_le_u32_e32 vcc, s12, v125
	s_or_b32 s12, s64, 48
	s_nop 0
	v_cndmask_b32_e32 v74, 0, v31, vcc
	v_cmp_le_u32_e32 vcc, s12, v125
	s_or_b32 s12, s64, 50
	s_nop 0
	v_cndmask_b32_e32 v73, 0, v28, vcc
	v_cmp_le_u32_e32 vcc, s12, v125
	s_or_b32 s12, s64, 52
	s_nop 0
	v_cndmask_b32_e32 v72, 0, v29, vcc
	v_cmp_le_u32_e32 vcc, s12, v125
	s_or_b32 s12, s64, 54
	s_nop 0
	v_cndmask_b32_e32 v71, 0, v26, vcc
	v_cmp_le_u32_e32 vcc, s12, v125
	s_or_b32 s12, s64, 56
	s_nop 0
	v_cndmask_b32_e32 v70, 0, v27, vcc
	v_cmp_le_u32_e32 vcc, s12, v125
	s_or_b32 s12, s64, 58
	s_nop 0
	v_cndmask_b32_e32 v69, 0, v24, vcc
	v_cmp_le_u32_e32 vcc, s12, v125
	s_or_b32 s12, s64, 60
	s_nop 0
	v_cndmask_b32_e32 v68, 0, v25, vcc
	v_cmp_le_u32_e32 vcc, s12, v125
	s_or_b32 s12, s64, 62
	s_nop 0
	v_cndmask_b32_e32 v67, 0, v22, vcc
	v_cmp_le_u32_e32 vcc, s12, v125
	s_or_b32 s12, s64, 0x42
	s_nop 0
	v_cndmask_b32_e32 v66, 0, v23, vcc
	v_cmp_le_u32_e32 vcc, s12, v125
	s_or_b32 s12, s64, 0x44
	s_nop 0
	v_cndmask_b32_e32 v65, 0, v3, vcc
	v_cmp_le_u32_e32 vcc, s12, v125
	s_or_b32 s12, s64, 0x46
	s_nop 0
	v_cndmask_b32_e32 v64, 0, v48, vcc
	v_cmp_le_u32_e32 vcc, s12, v125
	s_or_b32 s12, s64, 0x48
	s_nop 0
	v_cndmask_b32_e32 v49, 0, v49, vcc
	v_cmp_le_u32_e32 vcc, s12, v125
	s_or_b32 s12, s64, 0x4a
	s_nop 0
	v_cndmask_b32_e32 v48, 0, v46, vcc
	v_cmp_le_u32_e32 vcc, s12, v125
	s_or_b32 s12, s64, 0x4c
	s_nop 0
	v_cndmask_b32_e32 v46, 0, v47, vcc
	v_cmp_le_u32_e32 vcc, s12, v125
	s_or_b32 s12, s64, 0x4e
	s_nop 0
	v_cndmask_b32_e32 v35, 0, v44, vcc
	v_cmp_le_u32_e32 vcc, s12, v125
	s_or_b32 s12, s64, 0x50
	s_nop 0
	v_cndmask_b32_e32 v34, 0, v45, vcc
	v_cmp_le_u32_e32 vcc, s12, v125
	s_or_b32 s12, s64, 0x52
	s_nop 0
	v_cndmask_b32_e32 v33, 0, v40, vcc
	v_cmp_le_u32_e32 vcc, s12, v125
	s_or_b32 s12, s64, 0x54
	s_nop 0
	v_cndmask_b32_e32 v32, 0, v41, vcc
	v_cmp_le_u32_e32 vcc, s12, v125
	s_or_b32 s12, s64, 0x56
	s_nop 0
	v_cndmask_b32_e32 v31, 0, v38, vcc
	v_cmp_le_u32_e32 vcc, s12, v125
	s_or_b32 s12, s64, 0x58
	s_nop 0
	v_cndmask_b32_e32 v30, 0, v39, vcc
	v_cmp_le_u32_e32 vcc, s12, v125
	s_or_b32 s12, s64, 0x5a
	s_nop 0
	v_cndmask_b32_e32 v28, 0, v36, vcc
	v_cmp_le_u32_e32 vcc, s12, v125
	s_or_b32 s12, s64, 0x5c
	s_nop 0
	v_cndmask_b32_e32 v23, 0, v37, vcc
	v_cmp_le_u32_e32 vcc, s12, v125
	s_or_b32 s12, s64, 0x5e
	s_nop 0
	v_cndmask_b32_e32 v22, 0, v42, vcc
	v_cmp_le_u32_e32 vcc, s12, v125
	s_or_b32 s12, s64, 0x62
	s_nop 0
	v_cndmask_b32_e32 v21, 0, v43, vcc
	v_cmp_le_u32_e32 vcc, s12, v125
	s_or_b32 s12, s64, 0x64
	s_nop 0
	v_cndmask_b32_e32 v20, 0, v1, vcc
	v_cmp_le_u32_e32 vcc, s12, v125
	s_or_b32 s12, s64, 0x66
	v_subrev_u32_e32 v1, s64, v125
	v_cndmask_b32_e32 v19, 0, v62, vcc
	v_cmp_le_u32_e32 vcc, s12, v125
	s_or_b32 s12, s64, 0x68
	v_add_u32_e32 v5, 2, v1
	v_cndmask_b32_e32 v18, 0, v63, vcc
	v_cmp_le_u32_e32 vcc, s12, v125
	s_or_b32 s12, s64, 0x6a
	v_lshlrev_b32_e32 v1, 8, v96
	v_cndmask_b32_e32 v17, 0, v60, vcc
	v_cmp_le_u32_e32 vcc, s12, v125
	s_or_b32 s12, s64, 0x6c
	v_cmp_lt_u32_e64 s[18:19], 1, v5
	v_cndmask_b32_e32 v16, 0, v61, vcc
	v_cmp_le_u32_e32 vcc, s12, v125
	s_or_b32 s12, s64, 0x6e
	v_cmp_lt_u32_e64 s[16:17], 33, v5
	v_cndmask_b32_e32 v15, 0, v58, vcc
	v_cmp_le_u32_e32 vcc, s12, v125
	s_or_b32 s12, s64, 0x70
	s_nop 0
	v_cndmask_b32_e32 v14, 0, v59, vcc
	v_cmp_le_u32_e32 vcc, s12, v125
	s_or_b32 s12, s64, 0x72
	s_nop 0
	v_cndmask_b32_e32 v13, 0, v56, vcc
	v_cmp_le_u32_e32 vcc, s12, v125
	s_or_b32 s12, s64, 0x74
; #define PAIR_XCHG(SLOT, TAG, MINE, OTHER) do { const unsigned tg_ = (seq << 8) | (unsigned)(TAG); if (lane == 0) xw[w * 4 + (SLOT)] = ((MINE) << 16) | tg_; \
;             unsigned v_; do { v_ = xw[(w ^ 1) * 4 + (SLOT)]; } while ((v_ & 0xffffu) != tg_); OTHER = v_ >> 16; } while (0)
; __device__ __forceinline__ void attn_item(const Ptrs& P, unsigned char* lds, int b, int tq0, int tid) {
;     ...
;         unsigned th = 0u;
;     ...
;             const unsigned cand = th | (1u << bit); unsigned cnt = 0, oth;
; #pragma unroll
;             for (int k = 0; k < 4; ++k) if (16 * k < nact) {
; #pragma unroll
;                 for (int r = 16 * k; r < 16 * k + 16; ++r) cnt += (unsigned)__popcll(__ballot(k2[r] >= cand)); }
;             PAIR_XCHG(bit & 1, 1 + bit, cnt, oth);
;             cnt += oth;
;             if (cnt >= 256u) th = cand;
;             if (cnt == 256u) break;
;         }
	s_nop 0
	v_cndmask_b32_e32 v12, 0, v57, vcc
	v_cmp_le_u32_e32 vcc, s12, v125
	s_or_b32 s12, s64, 0x76
	s_nop 0
	v_cndmask_b32_e32 v11, 0, v54, vcc
	v_cmp_le_u32_e32 vcc, s12, v125
	s_or_b32 s12, s64, 0x78
	s_nop 0
	v_cndmask_b32_e32 v10, 0, v55, vcc
	v_cmp_le_u32_e32 vcc, s12, v125
	s_or_b32 s12, s64, 0x7a
	s_nop 0
	v_cndmask_b32_e32 v9, 0, v52, vcc
	v_cmp_le_u32_e32 vcc, s12, v125
	s_or_b32 s12, s64, 0x7c
	s_nop 0
	v_cndmask_b32_e32 v8, 0, v53, vcc
	v_cmp_le_u32_e32 vcc, s12, v125
	s_or_b32 s12, s64, 0x7e
	s_nop 0
	v_cndmask_b32_e32 v7, 0, v50, vcc
	v_cmp_le_u32_e32 vcc, s12, v125
	s_lshl_b32 s12, s62, 4
	s_add_i32 s74, s12, 0
	s_movk_i32 s12, 0x41
	v_cmp_lt_u32_e64 s[14:15], s12, v5
	s_movk_i32 s12, 0x61
	v_cndmask_b32_e32 v3, 0, v51, vcc
	s_add_i32 s74, s74, 0x24000
	v_cmp_lt_u32_e32 vcc, s12, v5
	v_mov_b32_e32 v5, 0
	v_max3_u32 v24, v6, v95, v94
	v_max3_u32 v24, v24, v93, v92
	v_max3_u32 v24, v24, v91, v90
	v_max3_u32 v24, v24, v89, v88
	v_max3_u32 v24, v24, v87, v86
	v_max3_u32 v24, v24, v85, v84
	v_max3_u32 v24, v24, v83, v82
	v_max3_u32 v24, v24, v81, v4
	v_max3_u32 v24, v24, v80, v79
	v_max3_u32 v24, v24, v78, v77
	v_max3_u32 v24, v24, v76, v75
	v_max3_u32 v24, v24, v74, v73
	v_max3_u32 v24, v24, v72, v71
	v_max3_u32 v24, v24, v70, v69
	v_max3_u32 v24, v24, v68, v67
	v_max3_u32 v24, v24, v66, v2
	v_max3_u32 v24, v24, v65, v64
	v_max3_u32 v24, v24, v49, v48
	v_max3_u32 v24, v24, v46, v35
	v_max3_u32 v24, v24, v34, v33
	v_max3_u32 v24, v24, v32, v31
	v_max3_u32 v24, v24, v30, v28
	v_max3_u32 v24, v24, v23, v22
	v_max3_u32 v24, v24, v21, v0
	v_max3_u32 v24, v24, v20, v19
	v_max3_u32 v24, v24, v18, v17
	v_max3_u32 v24, v24, v16, v15
	v_max3_u32 v24, v24, v14, v13
	v_max3_u32 v24, v24, v12, v11
	v_max3_u32 v24, v24, v10, v9
	v_max3_u32 v24, v24, v8, v7
	v_max3_u32 v24, v24, v3, v3
	s_nop 1
	v_max_u32_dpp v24, v24, v24 row_ror:1 row_mask:0xf bank_mask:0xf
	s_nop 1
	v_max_u32_dpp v24, v24, v24 row_ror:2 row_mask:0xf bank_mask:0xf
	s_nop 1
	v_max_u32_dpp v24, v24, v24 row_ror:4 row_mask:0xf bank_mask:0xf
	s_nop 1
	v_max_u32_dpp v24, v24, v24 row_ror:8 row_mask:0xf bank_mask:0xf
	s_nop 1
	v_readlane_b32 s84, v24, 0
	v_readlane_b32 s85, v24, 16
	v_readlane_b32 s87, v24, 32
	v_readlane_b32 s88, v24, 48
	v_readfirstlane_b32 s86, v1
	s_nop 3
	s_max_u32 s84, s84, s85
	s_max_u32 s87, s87, s88
	s_max_u32 s84, s84, s87
	s_lshr_b32 s84, s84, 16
	s_or_b32 s12, s86, 43
	s_lshl_b32 s13, s84, 16
	s_or_b32 s13, s13, s12
	v_mov_b32_e32 v27, s13
	s_add_i32 s89, s74, 12
	v_mov_b32_e32 v36, s89
	s_xor_b32 s89, s83, 4
	s_lshl_b32 s89, s89, 2
	s_add_i32 s88, s89, 0x24000
	s_add_i32 s89, s88, 12
	v_mov_b32_e32 v37, s89
	s_mov_b64 s[44:45], exec
	s_mov_b64 exec, s[4:5]
	ds_write_b32 v36, v27
	s_mov_b64 exec, s[44:45]
.Lbis_mspin:
	ds_read_b32 v27, v37
	s_waitcnt lgkmcnt(0)
	v_readfirstlane_b32 s13, v27
	s_nop 3
	s_and_b32 s89, s13, 0xffff
	s_cmp_eq_u32 s89, s12
	s_cbranch_scc0 .Lbis_mspin
	s_lshr_b32 s13, s13, 16
	s_max_u32 s84, s84, s13
	s_mov_b32 s85, 0
	s_mov_b32 s87, s74
.Lbis_loop:
	s_lshl_b32 s12, 1, s75
	s_or_b32 s12, s85, s12
	s_lshr_b32 s13, s12, 16
	s_cmp_gt_u32 s13, s84
	s_cbranch_scc1 .Lbis_next
	v_mov_b32_e32 v24, s12
	v_mov_b32_e32 v25, 0
	s_cmp_eq_u64 s[18:19], 0
	s_cbranch_scc1 .Lbis_cnt_done
	v_cmp_ge_u32_e64 s[78:79], v6, v24
	v_cmp_ge_u32_e64 s[90:91], v95, v24
	v_cmp_ge_u32_e64 s[92:93], v94, v24
	v_addc_co_u32_e64 v25, s[94:95], 0, v25, s[78:79]
	v_cmp_ge_u32_e64 s[78:79], v93, v24
	v_addc_co_u32_e64 v25, s[94:95], 0, v25, s[90:91]
	v_cmp_ge_u32_e64 s[90:91], v92, v24
	v_addc_co_u32_e64 v25, s[94:95], 0, v25, s[92:93]
	v_cmp_ge_u32_e64 s[92:93], v91, v24
	v_addc_co_u32_e64 v25, s[94:95], 0, v25, s[78:79]
	v_cmp_ge_u32_e64 s[78:79], v90, v24
	v_addc_co_u32_e64 v25, s[94:95], 0, v25, s[90:91]
	v_cmp_ge_u32_e64 s[90:91], v89, v24
	v_addc_co_u32_e64 v25, s[94:95], 0, v25, s[92:93]
	v_cmp_ge_u32_e64 s[92:93], v88, v24
	v_addc_co_u32_e64 v25, s[94:95], 0, v25, s[78:79]
	v_cmp_ge_u32_e64 s[78:79], v87, v24
	v_addc_co_u32_e64 v25, s[94:95], 0, v25, s[90:91]
	v_cmp_ge_u32_e64 s[90:91], v86, v24
	v_addc_co_u32_e64 v25, s[94:95], 0, v25, s[92:93]
	v_cmp_ge_u32_e64 s[92:93], v85, v24
	v_addc_co_u32_e64 v25, s[94:95], 0, v25, s[78:79]
	v_cmp_ge_u32_e64 s[78:79], v84, v24
	v_addc_co_u32_e64 v25, s[94:95], 0, v25, s[90:91]
	v_cmp_ge_u32_e64 s[90:91], v83, v24
	v_addc_co_u32_e64 v25, s[94:95], 0, v25, s[92:93]
	v_cmp_ge_u32_e64 s[92:93], v82, v24
	v_addc_co_u32_e64 v25, s[94:95], 0, v25, s[78:79]
	v_cmp_ge_u32_e64 s[78:79], v81, v24
	v_addc_co_u32_e64 v25, s[94:95], 0, v25, s[90:91]
	v_addc_co_u32_e64 v25, s[94:95], 0, v25, s[92:93]
	v_addc_co_u32_e64 v25, s[94:95], 0, v25, s[78:79]
	s_cmp_eq_u64 s[16:17], 0
	s_cbranch_scc1 .Lbis_cnt_done
	v_cmp_ge_u32_e64 s[78:79], v4, v24
	v_cmp_ge_u32_e64 s[90:91], v80, v24
	v_cmp_ge_u32_e64 s[92:93], v79, v24
	v_addc_co_u32_e64 v25, s[94:95], 0, v25, s[78:79]
	v_cmp_ge_u32_e64 s[78:79], v78, v24
	v_addc_co_u32_e64 v25, s[94:95], 0, v25, s[90:91]
	v_cmp_ge_u32_e64 s[90:91], v77, v24
	v_addc_co_u32_e64 v25, s[94:95], 0, v25, s[92:93]
	v_cmp_ge_u32_e64 s[92:93], v76, v24
	v_addc_co_u32_e64 v25, s[94:95], 0, v25, s[78:79]
	v_cmp_ge_u32_e64 s[78:79], v75, v24
	v_addc_co_u32_e64 v25, s[94:95], 0, v25, s[90:91]
	v_cmp_ge_u32_e64 s[90:91], v74, v24
	v_addc_co_u32_e64 v25, s[94:95], 0, v25, s[92:93]
	v_cmp_ge_u32_e64 s[92:93], v73, v24
	v_addc_co_u32_e64 v25, s[94:95], 0, v25, s[78:79]
	v_cmp_ge_u32_e64 s[78:79], v72, v24
	v_addc_co_u32_e64 v25, s[94:95], 0, v25, s[90:91]
	v_cmp_ge_u32_e64 s[90:91], v71, v24
	v_addc_co_u32_e64 v25, s[94:95], 0, v25, s[92:93]
	v_cmp_ge_u32_e64 s[92:93], v70, v24
	v_addc_co_u32_e64 v25, s[94:95], 0, v25, s[78:79]
	v_cmp_ge_u32_e64 s[78:79], v69, v24
	v_addc_co_u32_e64 v25, s[94:95], 0, v25, s[90:91]
	v_cmp_ge_u32_e64 s[90:91], v68, v24
	v_addc_co_u32_e64 v25, s[94:95], 0, v25, s[92:93]
	v_cmp_ge_u32_e64 s[92:93], v67, v24
	v_addc_co_u32_e64 v25, s[94:95], 0, v25, s[78:79]
	v_cmp_ge_u32_e64 s[78:79], v66, v24
	v_addc_co_u32_e64 v25, s[94:95], 0, v25, s[90:91]
	v_addc_co_u32_e64 v25, s[94:95], 0, v25, s[92:93]
	v_addc_co_u32_e64 v25, s[94:95], 0, v25, s[78:79]
	s_cmp_eq_u64 s[14:15], 0
	s_cbranch_scc1 .Lbis_cnt_done
; #define PAIR_XCHG(SLOT, TAG, MINE, OTHER) do { const unsigned tg_ = (seq << 8) | (unsigned)(TAG); if (lane == 0) xw[w * 4 + (SLOT)] = ((MINE) << 16) | tg_; \
;             unsigned v_; do { v_ = xw[(w ^ 1) * 4 + (SLOT)]; } while ((v_ & 0xffffu) != tg_); OTHER = v_ >> 16; } while (0)
; __device__ __forceinline__ void attn_item(const Ptrs& P, unsigned char* lds, int b, int tq0, int tid) {
;     ...
;             const unsigned cand = th | (1u << bit); unsigned cnt = 0, oth;
; #pragma unroll
;             for (int k = 0; k < 4; ++k) if (16 * k < nact) {
; #pragma unroll
;                 for (int r = 16 * k; r < 16 * k + 16; ++r) cnt += (unsigned)__popcll(__ballot(k2[r] >= cand)); }
;             PAIR_XCHG(bit & 1, 1 + bit, cnt, oth);
;             cnt += oth;
;             if (cnt >= 256u) th = cand;
	v_cmp_ge_u32_e64 s[78:79], v2, v24
	v_cmp_ge_u32_e64 s[90:91], v65, v24
	v_cmp_ge_u32_e64 s[92:93], v64, v24
	v_addc_co_u32_e64 v25, s[94:95], 0, v25, s[78:79]
	v_cmp_ge_u32_e64 s[78:79], v49, v24
	v_addc_co_u32_e64 v25, s[94:95], 0, v25, s[90:91]
	v_cmp_ge_u32_e64 s[90:91], v48, v24
	v_addc_co_u32_e64 v25, s[94:95], 0, v25, s[92:93]
	v_cmp_ge_u32_e64 s[92:93], v46, v24
	v_addc_co_u32_e64 v25, s[94:95], 0, v25, s[78:79]
	v_cmp_ge_u32_e64 s[78:79], v35, v24
	v_addc_co_u32_e64 v25, s[94:95], 0, v25, s[90:91]
	v_cmp_ge_u32_e64 s[90:91], v34, v24
	v_addc_co_u32_e64 v25, s[94:95], 0, v25, s[92:93]
	v_cmp_ge_u32_e64 s[92:93], v33, v24
	v_addc_co_u32_e64 v25, s[94:95], 0, v25, s[78:79]
	v_cmp_ge_u32_e64 s[78:79], v32, v24
	v_addc_co_u32_e64 v25, s[94:95], 0, v25, s[90:91]
	v_cmp_ge_u32_e64 s[90:91], v31, v24
	v_addc_co_u32_e64 v25, s[94:95], 0, v25, s[92:93]
	v_cmp_ge_u32_e64 s[92:93], v30, v24
	v_addc_co_u32_e64 v25, s[94:95], 0, v25, s[78:79]
	v_cmp_ge_u32_e64 s[78:79], v28, v24
	v_addc_co_u32_e64 v25, s[94:95], 0, v25, s[90:91]
	v_cmp_ge_u32_e64 s[90:91], v23, v24
	v_addc_co_u32_e64 v25, s[94:95], 0, v25, s[92:93]
	v_cmp_ge_u32_e64 s[92:93], v22, v24
	v_addc_co_u32_e64 v25, s[94:95], 0, v25, s[78:79]
	v_cmp_ge_u32_e64 s[78:79], v21, v24
	v_addc_co_u32_e64 v25, s[94:95], 0, v25, s[90:91]
	v_addc_co_u32_e64 v25, s[94:95], 0, v25, s[92:93]
	v_addc_co_u32_e64 v25, s[94:95], 0, v25, s[78:79]
	s_cmp_eq_u64 vcc, 0
	s_cbranch_scc1 .Lbis_cnt_done
	v_cmp_ge_u32_e64 s[78:79], v0, v24
	v_cmp_ge_u32_e64 s[90:91], v20, v24
	v_cmp_ge_u32_e64 s[92:93], v19, v24
	v_addc_co_u32_e64 v25, s[94:95], 0, v25, s[78:79]
	v_cmp_ge_u32_e64 s[78:79], v18, v24
	v_addc_co_u32_e64 v25, s[94:95], 0, v25, s[90:91]
	v_cmp_ge_u32_e64 s[90:91], v17, v24
	v_addc_co_u32_e64 v25, s[94:95], 0, v25, s[92:93]
	v_cmp_ge_u32_e64 s[92:93], v16, v24
	v_addc_co_u32_e64 v25, s[94:95], 0, v25, s[78:79]
	v_cmp_ge_u32_e64 s[78:79], v15, v24
	v_addc_co_u32_e64 v25, s[94:95], 0, v25, s[90:91]
	v_cmp_ge_u32_e64 s[90:91], v14, v24
	v_addc_co_u32_e64 v25, s[94:95], 0, v25, s[92:93]
	v_cmp_ge_u32_e64 s[92:93], v13, v24
	v_addc_co_u32_e64 v25, s[94:95], 0, v25, s[78:79]
	v_cmp_ge_u32_e64 s[78:79], v12, v24
	v_addc_co_u32_e64 v25, s[94:95], 0, v25, s[90:91]
	v_cmp_ge_u32_e64 s[90:91], v11, v24
	v_addc_co_u32_e64 v25, s[94:95], 0, v25, s[92:93]
	v_cmp_ge_u32_e64 s[92:93], v10, v24
	v_addc_co_u32_e64 v25, s[94:95], 0, v25, s[78:79]
	v_cmp_ge_u32_e64 s[78:79], v9, v24
	v_addc_co_u32_e64 v25, s[94:95], 0, v25, s[90:91]
	v_cmp_ge_u32_e64 s[90:91], v8, v24
	v_addc_co_u32_e64 v25, s[94:95], 0, v25, s[92:93]
	v_cmp_ge_u32_e64 s[92:93], v7, v24
	v_addc_co_u32_e64 v25, s[94:95], 0, v25, s[78:79]
	v_cmp_ge_u32_e64 s[78:79], v3, v24
	v_addc_co_u32_e64 v25, s[94:95], 0, v25, s[90:91]
	v_addc_co_u32_e64 v25, s[94:95], 0, v25, s[92:93]
	v_addc_co_u32_e64 v25, s[94:95], 0, v25, s[78:79]
.Lbis_cnt_done:
	s_add_i32 s13, s75, 1
	s_or_b32 s13, s86, s13
	v_add_u32_dpp v25, v25, v25 row_ror:1 row_mask:0xf bank_mask:0xf
	s_nop 1
	v_add_u32_dpp v25, v25, v25 row_ror:2 row_mask:0xf bank_mask:0xf
	s_nop 1
	v_add_u32_dpp v25, v25, v25 row_ror:4 row_mask:0xf bank_mask:0xf
	s_nop 1
	v_add_u32_dpp v25, v25, v25 row_ror:8 row_mask:0xf bank_mask:0xf
	v_mov_b32_e32 v36, s87
	v_mov_b32_e32 v37, s88
	v_readlane_b32 s78, v25, 0
	v_readlane_b32 s79, v25, 16
	v_readlane_b32 s90, v25, 32
	v_readlane_b32 s91, v25, 48
	s_mov_b64 s[44:45], exec
	s_nop 2
	s_add_i32 s78, s78, s79
	s_add_i32 s90, s90, s91
	s_add_i32 s78, s78, s90
	s_lshl_b32 s20, s78, 16
	s_or_b32 s20, s20, s13
	v_mov_b32_e32 v27, s20
	s_mov_b64 exec, s[4:5]
	ds_write_b32 v36, v27
	s_mov_b64 exec, s[44:45]
; #define PAIR_XCHG(SLOT, TAG, MINE, OTHER) do { const unsigned tg_ = (seq << 8) | (unsigned)(TAG); if (lane == 0) xw[w * 4 + (SLOT)] = ((MINE) << 16) | tg_; \
;             unsigned v_; do { v_ = xw[(w ^ 1) * 4 + (SLOT)]; } while ((v_ & 0xffffu) != tg_); OTHER = v_ >> 16; } while (0)
; __device__ __forceinline__ void attn_item(const Ptrs& P, unsigned char* lds, int b, int tq0, int tid) {
;     ...
;             const unsigned cand = th | (1u << bit); unsigned cnt = 0, oth;
; #pragma unroll
;             for (int k = 0; k < 4; ++k) if (16 * k < nact) {
; #pragma unroll
;                 for (int r = 16 * k; r < 16 * k + 16; ++r) cnt += (unsigned)__popcll(__ballot(k2[r] >= cand)); }
;             PAIR_XCHG(bit & 1, 1 + bit, cnt, oth);
;             cnt += oth;
;             if (cnt >= 256u) th = cand;
;             if (cnt == 256u) break;
;         }
;         unsigned cg = 0, ce = 0;
; #pragma unroll
;         for (int k = 0; k < 4; ++k) if (16 * k < nact) {
; #pragma unroll
;             for (int r = 16 * k; r < 16 * k + 16; ++r) { cg += (k2[r] > th) ? 1u : 0u; ce += (k2[r] == th) ? 1u : 0u; } }
.Lbis_spin:
	ds_read_b32 v27, v37
	s_waitcnt lgkmcnt(0)
	v_readfirstlane_b32 s20, v27
	s_nop 3
	s_and_b32 s89, s20, 0xffff
	s_cmp_eq_u32 s89, s13
	s_cbranch_scc0 .Lbis_spin
	s_lshr_b32 s20, s20, 16
	s_add_i32 s78, s78, s20
	s_xor_b32 s87, s87, 4
	s_xor_b32 s88, s88, 4
	s_cmp_gt_u32 s78, 0xff
	s_cselect_b32 s85, s12, s85
	s_cmp_eq_u32 s78, 0x100
	s_cbranch_scc1 .Lbis_done
.Lbis_next:
	s_cmp_eq_u32 s75, 0
	s_cbranch_scc1 .Lbis_done
	s_sub_i32 s75, s75, 1
	s_branch .Lbis_loop
.Lbis_done:
	v_mov_b32_e32 v5, s85
	s_nop 0
	s_nop 0
	s_nop 0
	s_nop 0
	s_nop 0
	s_nop 0
	s_nop 0
	s_nop 0
	s_nop 0
	s_or_b64 exec, exec, s[72:73]
	v_mov_b32_e32 v25, 0
	v_mov_b32_e32 v26, 0
	s_and_saveexec_b64 s[44:45], s[18:19]
	s_cbranch_execz .LBB0_507
	v_cmp_gt_u32_e64 s[12:13], v95, v5
	s_nop 1
	v_cndmask_b32_e64 v24, 0, 1, s[12:13]
	v_cmp_gt_u32_e64 s[12:13], v6, v5
	s_nop 1
	v_addc_co_u32_e64 v24, s[12:13], 0, v24, s[12:13]
	v_cmp_eq_u32_e64 s[12:13], v95, v5
	s_nop 1
	v_cndmask_b32_e64 v25, 0, 1, s[12:13]
	v_cmp_eq_u32_e64 s[12:13], v6, v5
	s_nop 1
	v_addc_co_u32_e64 v25, s[12:13], 0, v25, s[12:13]
	v_cmp_gt_u32_e64 s[12:13], v94, v5
	s_nop 1
	v_cndmask_b32_e64 v26, 0, 1, s[12:13]
	v_cmp_eq_u32_e64 s[12:13], v94, v5
	s_nop 1
	v_cndmask_b32_e64 v27, 0, 1, s[12:13]
	v_cmp_gt_u32_e64 s[12:13], v93, v5
	s_nop 1
	v_addc_co_u32_e64 v24, s[12:13], v24, v26, s[12:13]
	v_cmp_eq_u32_e64 s[12:13], v93, v5
	s_nop 1
	v_addc_co_u32_e64 v25, s[12:13], v25, v27, s[12:13]
	v_cmp_gt_u32_e64 s[12:13], v92, v5
	s_nop 1
	v_cndmask_b32_e64 v26, 0, 1, s[12:13]
	v_cmp_eq_u32_e64 s[12:13], v92, v5
	s_nop 1
	v_cndmask_b32_e64 v27, 0, 1, s[12:13]
	v_cmp_gt_u32_e64 s[12:13], v91, v5
	s_nop 1
	v_addc_co_u32_e64 v24, s[12:13], v24, v26, s[12:13]
	v_cmp_eq_u32_e64 s[12:13], v91, v5
	s_nop 1
	v_addc_co_u32_e64 v25, s[12:13], v25, v27, s[12:13]
	v_cmp_gt_u32_e64 s[12:13], v90, v5
	s_nop 1
	v_cndmask_b32_e64 v26, 0, 1, s[12:13]
	v_cmp_eq_u32_e64 s[12:13], v90, v5
	s_nop 1
	v_cndmask_b32_e64 v27, 0, 1, s[12:13]
	v_cmp_gt_u32_e64 s[12:13], v89, v5
	s_nop 1
	v_addc_co_u32_e64 v24, s[12:13], v24, v26, s[12:13]
	v_cmp_eq_u32_e64 s[12:13], v89, v5
	s_nop 1
	v_addc_co_u32_e64 v25, s[12:13], v25, v27, s[12:13]
	v_cmp_gt_u32_e64 s[12:13], v88, v5
	s_nop 1
	v_cndmask_b32_e64 v26, 0, 1, s[12:13]
	v_cmp_eq_u32_e64 s[12:13], v88, v5
	s_nop 1
	v_cndmask_b32_e64 v27, 0, 1, s[12:13]
	v_cmp_gt_u32_e64 s[12:13], v87, v5
	s_nop 1
	v_addc_co_u32_e64 v24, s[12:13], v24, v26, s[12:13]
	v_cmp_eq_u32_e64 s[12:13], v87, v5
	s_nop 1
	v_addc_co_u32_e64 v25, s[12:13], v25, v27, s[12:13]
	v_cmp_gt_u32_e64 s[12:13], v86, v5
	s_nop 1
	v_cndmask_b32_e64 v26, 0, 1, s[12:13]
	v_cmp_eq_u32_e64 s[12:13], v86, v5
	s_nop 1
	v_cndmask_b32_e64 v27, 0, 1, s[12:13]
	v_cmp_gt_u32_e64 s[12:13], v85, v5
	s_nop 1
	v_addc_co_u32_e64 v24, s[12:13], v24, v26, s[12:13]
	v_cmp_eq_u32_e64 s[12:13], v85, v5
	s_nop 1
	v_addc_co_u32_e64 v25, s[12:13], v25, v27, s[12:13]
	v_cmp_gt_u32_e64 s[12:13], v84, v5
	s_nop 1
	v_cndmask_b32_e64 v26, 0, 1, s[12:13]
	v_cmp_eq_u32_e64 s[12:13], v84, v5
	s_nop 1
	v_cndmask_b32_e64 v27, 0, 1, s[12:13]
	v_cmp_gt_u32_e64 s[12:13], v83, v5
	s_nop 1
	v_addc_co_u32_e64 v24, s[12:13], v24, v26, s[12:13]
	v_cmp_eq_u32_e64 s[12:13], v83, v5
	s_nop 1
	v_addc_co_u32_e64 v25, s[12:13], v25, v27, s[12:13]
	v_cmp_gt_u32_e64 s[12:13], v82, v5
	s_nop 1
	v_cndmask_b32_e64 v26, 0, 1, s[12:13]
	v_cmp_eq_u32_e64 s[12:13], v82, v5
	s_nop 1
	v_cndmask_b32_e64 v27, 0, 1, s[12:13]
	v_cmp_gt_u32_e64 s[12:13], v81, v5
	s_nop 1
	v_addc_co_u32_e64 v26, s[12:13], v24, v26, s[12:13]
	v_cmp_eq_u32_e64 s[12:13], v81, v5
	s_nop 1
	v_addc_co_u32_e64 v25, s[12:13], v25, v27, s[12:13]
	s_or_b64 exec, exec, s[44:45]
	s_and_saveexec_b64 s[44:45], s[16:17]
	s_cbranch_execnz .LBB0_508

; __device__ __forceinline__ f32x4 mfma16(bf16x8 a, bf16x8 b, f32x4 c) { const f32x4 r = __builtin_amdgcn_mfma_f32_16x16x32_bf16(a, b, c, 0, 0, 0); asm volatile("" :: "v"(a), "v"(b)); return r; }
; __device__ __forceinline__ void attn_item(const Ptrs& P, unsigned char* lds, int b, int tq0, int tid) {
;     ...
;         for (int k2 = 0; k2 < 2; ++k2) {
;             const int slot = slot0 + 32 * ck + 16 * k2 + r16; const bool valid = slot < nsel; const int idx = (int)sel[q * 256 + slot];
;             int dist = tq - idx; dist = dist > 128 ? 128 : dist; dist = dist < 0 ? 0 : dist;
;             const f32x4 bb = *(const f32x4*)(P.BT + dist * 16 + 4 * g);
;             const bf16_t* kp = stw + (16 * k2 + r16) * SP + 8 * g;
;             f32x4 a = {0.f, 0.f, 0.f, 0.f};
; #pragma unroll
;             for (int ks = 0; ks < 8; ++ks) a = mfma16(Af[ks], *(const bf16x8*)(kp + 32 * ks), a);
; #pragma unroll
;             for (int j = 0; j < 4; ++j) a[j] = valid ? a[j] * 0.0625f + bb[j] : -1e30f;
;             sc[k2] = a;
.LBB0_926:
	s_nop 0
	s_nop 0
	s_nop 0
	v_add_u32_e32 v233, s13, v226
	s_waitcnt lgkmcnt(0)
	v_add_u32_e32 v164, 0x21100, v233
	ds_read_u16 v164, v164
	ds_read_b128 v[238:241], v231
	ds_read_b128 v[248:251], v231 offset:64
	v_cmp_gt_u32_e32 vcc, v227, v221
	v_add_u32_e32 v253, 16, v227
	s_waitcnt lgkmcnt(1)
	v_mfma_f32_16x16x32_bf16 v[242:245], v[0:3], v[238:241], 0
	ds_read_b128 v[238:241], v231 offset:128
	v_sub_u32_e32 v164, v220, v164
	v_med3_i32 v164, v164, 0, v215
	v_lshlrev_b32_e32 v164, 6, v164
	v_add_u32_e64 v192, v176, v164
	ds_read_b128 v[234:237], v192
	s_waitcnt lgkmcnt(2)
	v_mfma_f32_16x16x32_bf16 v[242:245], v[4:7], v[248:251], v[242:245]
	ds_read_b128 v[248:251], v231 offset:192
	s_waitcnt lgkmcnt(2)
	v_mfma_f32_16x16x32_bf16 v[242:245], v[8:11], v[238:241], v[242:245]
	ds_read_b128 v[238:241], v231 offset:256
	s_waitcnt lgkmcnt(1)
	s_add_i32 s13, s13, 64
	v_mfma_f32_16x16x32_bf16 v[242:245], v[12:15], v[248:251], v[242:245]
	ds_read_b128 v[248:251], v231 offset:320
	s_waitcnt lgkmcnt(1)
	v_add_u32_e32 v227, 32, v227
	v_mfma_f32_16x16x32_bf16 v[242:245], v[16:19], v[238:241], v[242:245]
	ds_read_b128 v[238:241], v231 offset:384
	s_waitcnt lgkmcnt(1)
	s_cmp_eq_u32 s13, 0
	v_mfma_f32_16x16x32_bf16 v[242:245], v[20:23], v[248:251], v[242:245]
	ds_read_b128 v[248:251], v231 offset:448
	s_waitcnt lgkmcnt(1)
	v_mfma_f32_16x16x32_bf16 v[242:245], v[24:27], v[238:241], v[242:245]
	ds_read_b128 v[238:241], v231 offset:8448
	s_waitcnt lgkmcnt(1)
	v_mfma_f32_16x16x32_bf16 v[242:245], v[28:31], v[248:251], v[242:245]
	ds_read_b128 v[248:251], v231 offset:8512
	s_nop 6
	v_fmamk_f32 v164, v242, 0x3d800000, v234
	v_cndmask_b32_e32 v246, v164, v216, vcc
	v_fmamk_f32 v164, v243, 0x3d800000, v235
	v_cndmask_b32_e32 v247, v164, v216, vcc
	v_fmamk_f32 v164, v244, 0x3d800000, v236
	v_cndmask_b32_e32 v193, v164, v216, vcc
	v_add_u32_e32 v164, 0x21120, v233
	ds_read_u16 v164, v164
	v_fmac_f32_e32 v237, 0x3d800000, v245
	v_cndmask_b32_e32 v192, v237, v216, vcc
	s_waitcnt lgkmcnt(2)
	v_mfma_f32_16x16x32_bf16 v[242:245], v[0:3], v[238:241], 0
	ds_read_b128 v[238:241], v231 offset:8576
	v_cmp_gt_u32_e32 vcc, v253, v221
	s_waitcnt lgkmcnt(1)
	v_sub_u32_e32 v164, v220, v164
	v_med3_i32 v164, v164, 0, v215
	v_lshlrev_b32_e32 v164, 6, v164
	v_add_u32_e64 v234, v176, v164
	ds_read_b128 v[234:237], v234
	v_mfma_f32_16x16x32_bf16 v[242:245], v[4:7], v[248:251], v[242:245]
	ds_read_b128 v[248:251], v231 offset:8640
	s_waitcnt lgkmcnt(2)
	v_mfma_f32_16x16x32_bf16 v[242:245], v[8:11], v[238:241], v[242:245]
	ds_read_b128 v[238:241], v231 offset:8704
	s_waitcnt lgkmcnt(1)
	v_mfma_f32_16x16x32_bf16 v[242:245], v[12:15], v[248:251], v[242:245]
	ds_read_b128 v[248:251], v231 offset:8768
	s_waitcnt lgkmcnt(1)
	v_mfma_f32_16x16x32_bf16 v[242:245], v[16:19], v[238:241], v[242:245]
	ds_read_b128 v[238:241], v231 offset:8832
	s_waitcnt lgkmcnt(1)
	v_mfma_f32_16x16x32_bf16 v[242:245], v[20:23], v[248:251], v[242:245]
	ds_read_b128 v[248:251], v231 offset:8896
	s_waitcnt lgkmcnt(1)
	v_mfma_f32_16x16x32_bf16 v[242:245], v[24:27], v[238:241], v[242:245]
	s_waitcnt lgkmcnt(0)
	v_mfma_f32_16x16x32_bf16 v[242:245], v[28:31], v[248:251], v[242:245]
	s_nop 7
	v_fmamk_f32 v164, v242, 0x3d800000, v234
	v_cndmask_b32_e32 v233, v164, v216, vcc
	v_fmamk_f32 v164, v243, 0x3d800000, v235
	v_cndmask_b32_e32 v238, v164, v216, vcc
	v_fmamk_f32 v164, v244, 0x3d800000, v236
	v_cndmask_b32_e32 v244, v164, v216, vcc
	v_max_f32_e32 v164, v246, v233
	v_fmac_f32_e32 v237, 0x3d800000, v245
	v_cndmask_b32_e32 v236, v237, v216, vcc
	v_mov_b32_dpp v234, v164 row_ror:1 row_mask:0xf bank_mask:0xf bound_ctrl:1
	v_max_f32_e32 v234, v234, v234
	v_max_f32_e32 v164, v164, v234
	s_nop 1
	v_mov_b32_dpp v234, v164 row_ror:2 row_mask:0xf bank_mask:0xf bound_ctrl:1
	v_max_f32_e32 v234, v234, v234
	v_max_f32_e32 v164, v164, v234
	s_nop 1
	v_mov_b32_dpp v234, v164 row_ror:4 row_mask:0xf bank_mask:0xf bound_ctrl:1
	v_max_f32_e32 v234, v234, v234
	v_max_f32_e32 v164, v164, v234
	s_nop 1
	v_mov_b32_dpp v234, v164 row_ror:8 row_mask:0xf bank_mask:0xf bound_ctrl:1
	v_max3_f32 v164, v161, v164, v234
	v_sub_f32_e32 v234, v246, v164
	v_sub_f32_e32 v233, v233, v164
	v_mul_f32_e32 v234, 0x3fb8aa3b, v234
	v_mul_f32_e32 v233, 0x3fb8aa3b, v233
	v_exp_f32_e32 v235, v234
	v_exp_f32_e32 v239, v233
	v_cvt_pk_bf16_f32 v233, v235, v165
	ds_write_b16 v223, v233
	v_cvt_pk_bf16_f32 v233, v239, v165
	ds_write_b16 v224, v233 offset:32
	v_max_f32_e32 v233, v247, v238
	v_sub_f32_e32 v161, v161, v164
	v_mul_f32_e32 v161, 0x3fb8aa3b, v161
	v_mov_b32_dpp v234, v233 row_ror:1 row_mask:0xf bank_mask:0xf bound_ctrl:1
	v_max_f32_e32 v234, v234, v234
	v_max_f32_e32 v233, v233, v234
	v_exp_f32_e32 v161, v161
	s_nop 0
	v_mov_b32_dpp v234, v233 row_ror:2 row_mask:0xf bank_mask:0xf bound_ctrl:1
	v_max_f32_e32 v234, v234, v234
	v_max_f32_e32 v233, v233, v234
	s_nop 1
	v_mov_b32_dpp v234, v233 row_ror:4 row_mask:0xf bank_mask:0xf bound_ctrl:1
	v_max_f32_e32 v234, v234, v234
	v_max_f32_e32 v233, v233, v234
	s_nop 1
	v_mov_b32_dpp v234, v233 row_ror:8 row_mask:0xf bank_mask:0xf bound_ctrl:1
	v_max3_f32 v233, v160, v233, v234
	v_sub_f32_e32 v234, v247, v233
	v_sub_f32_e32 v237, v238, v233
	v_mul_f32_e32 v234, 0x3fb8aa3b, v234
	v_mul_f32_e32 v237, 0x3fb8aa3b, v237
	v_exp_f32_e32 v234, v234
	v_exp_f32_e32 v238, v237
	v_sub_f32_e32 v160, v160, v233
	v_mul_f32_e32 v160, 0x3fb8aa3b, v160
	v_exp_f32_e32 v160, v160
	v_pk_add_f32 v[240:241], v[234:235], v[238:239]
	v_cvt_pk_bf16_f32 v234, v234, v165
	ds_write_b16 v223, v234 offset:80
	v_cvt_pk_bf16_f32 v234, v238, v165
	ds_write_b16 v224, v234 offset:112
	v_max_f32_e32 v234, v193, v244
; __device__ __forceinline__ unsigned cvt_pk_bf16(float lo, float hi) { unsigned r; asm volatile("v_cvt_pk_bf16_f32 %0, %1, %2" : "=v"(r) : "v"(lo), "v"(hi)); return r; }
; __device__ __forceinline__ float row16_sum(float v) { v += dpp_f<0x121>(v); v += dpp_f<0x122>(v); v += dpp_f<0x124>(v); v += dpp_f<0x128>(v); return v; }
; __device__ __forceinline__ float row16_max(float v) { v = fmaxf(v, dpp_f<0x121>(v)); v = fmaxf(v, dpp_f<0x122>(v)); v = fmaxf(v, dpp_f<0x124>(v)); v = fmaxf(v, dpp_f<0x128>(v)); return v; }
; __device__ __forceinline__ void attn_item(const Ptrs& P, unsigned char* lds, int b, int tq0, int tid) {
;     ...
; #pragma unroll
;         for (int j = 0; j < 4; ++j) {
;             const float mn = fmaxf(mrun[j], row16_max(fmaxf(sc[0][j], sc[1][j])));
;             const float scale = __expf(mrun[j] - mn);
;             const float p0 = __expf(sc[0][j] - mn), p1 = __expf(sc[1][j] - mn);
;             lrun[j] = lrun[j] * scale + row16_sum(p0 + p1);
;             mrun[j] = mn;
; #pragma unroll
;             for (int dt = 0; dt < 16; ++dt) oacc[dt][j] *= scale;
;             Pw[(4 * g + j) * 40 + r16] = (bf16_t)(cvt_pk_bf16(p0, 0.f) & 0xffffu);
;             Pw[(4 * g + j) * 40 + 16 + r16] = (bf16_t)(cvt_pk_bf16(p1, 0.f) & 0xffffu);
;         }
	v_mov_b32_dpp v243, v241 row_ror:1 row_mask:0xf bank_mask:0xf bound_ctrl:1
	v_mov_b32_dpp v242, v240 row_ror:1 row_mask:0xf bank_mask:0xf bound_ctrl:1
	v_mov_b32_dpp v235, v234 row_ror:1 row_mask:0xf bank_mask:0xf bound_ctrl:1
	v_max_f32_e32 v235, v235, v235
	v_max_f32_e32 v234, v234, v235
	v_pk_add_f32 v[240:241], v[240:241], v[242:243]
	s_nop 0
	v_mov_b32_dpp v235, v234 row_ror:2 row_mask:0xf bank_mask:0xf bound_ctrl:1
	v_max_f32_e32 v235, v235, v235
	v_max_f32_e32 v234, v234, v235
	v_mov_b32_dpp v243, v241 row_ror:2 row_mask:0xf bank_mask:0xf bound_ctrl:1
	v_mov_b32_dpp v242, v240 row_ror:2 row_mask:0xf bank_mask:0xf bound_ctrl:1
	v_mov_b32_dpp v235, v234 row_ror:4 row_mask:0xf bank_mask:0xf bound_ctrl:1
	v_max_f32_e32 v235, v235, v235
	v_max_f32_e32 v234, v234, v235
	v_pk_add_f32 v[240:241], v[240:241], v[242:243]
	s_nop 0
	v_mov_b32_dpp v235, v234 row_ror:8 row_mask:0xf bank_mask:0xf bound_ctrl:1
	v_max3_f32 v234, v163, v234, v235
	v_sub_f32_e32 v163, v163, v234
	v_mul_f32_e32 v163, 0x3fb8aa3b, v163
	v_exp_f32_e32 v239, v163
	v_sub_f32_e32 v163, v193, v234
	v_mul_f32_e32 v163, 0x3fb8aa3b, v163
	v_sub_f32_e32 v193, v244, v234
	v_exp_f32_e32 v163, v163
	v_mul_f32_e32 v193, 0x3fb8aa3b, v193
	v_cvt_pk_bf16_f32 v235, v163, v165
	v_exp_f32_e32 v193, v193
	ds_write_b16 v223, v235 offset:160
	v_cvt_pk_bf16_f32 v235, v193, v165
	ds_write_b16 v224, v235 offset:192
	v_max_f32_e32 v235, v192, v236
	v_mov_b32_dpp v243, v241 row_ror:4 row_mask:0xf bank_mask:0xf bound_ctrl:1
	v_mov_b32_dpp v242, v240 row_ror:4 row_mask:0xf bank_mask:0xf bound_ctrl:1
	v_mov_b32_dpp v237, v235 row_ror:1 row_mask:0xf bank_mask:0xf bound_ctrl:1
	v_max_f32_e32 v237, v237, v237
	v_max_f32_e32 v235, v235, v237
	v_pk_add_f32 v[240:241], v[240:241], v[242:243]
	s_nop 0
	v_mov_b32_dpp v237, v235 row_ror:2 row_mask:0xf bank_mask:0xf bound_ctrl:1
	v_max_f32_e32 v237, v237, v237
	v_max_f32_e32 v235, v235, v237
	v_mov_b32_dpp v243, v241 row_ror:8 row_mask:0xf bank_mask:0xf bound_ctrl:1
	v_mov_b32_dpp v242, v240 row_ror:8 row_mask:0xf bank_mask:0xf bound_ctrl:1
	v_mov_b32_dpp v237, v235 row_ror:4 row_mask:0xf bank_mask:0xf bound_ctrl:1
	v_max_f32_e32 v237, v237, v237
	v_max_f32_e32 v235, v235, v237
	v_pk_add_f32 v[240:241], v[240:241], v[242:243]
	s_nop 0
	v_mov_b32_dpp v237, v235 row_ror:8 row_mask:0xf bank_mask:0xf bound_ctrl:1
	v_max3_f32 v235, v162, v235, v237
	v_sub_f32_e32 v162, v162, v235
	v_mul_f32_e32 v162, 0x3fb8aa3b, v162
	v_exp_f32_e32 v238, v162
	v_sub_f32_e32 v162, v192, v235
	v_sub_f32_e32 v192, v236, v235
	v_mul_f32_e32 v162, 0x3fb8aa3b, v162
	v_mul_f32_e32 v192, 0x3fb8aa3b, v192
	v_exp_f32_e32 v162, v162
	v_exp_f32_e32 v192, v192
	v_pk_fma_f32 v[190:191], v[190:191], v[160:161], v[240:241]
	v_pk_add_f32 v[236:237], v[162:163], v[192:193]
	s_nop 1
	v_mov_b32_dpp v241, v237 row_ror:1 row_mask:0xf bank_mask:0xf bound_ctrl:1
	v_mov_b32_dpp v240, v236 row_ror:1 row_mask:0xf bank_mask:0xf bound_ctrl:1
	v_pk_add_f32 v[236:237], v[236:237], v[240:241]
	s_nop 1
	v_mov_b32_dpp v241, v237 row_ror:2 row_mask:0xf bank_mask:0xf bound_ctrl:1
	v_mov_b32_dpp v240, v236 row_ror:2 row_mask:0xf bank_mask:0xf bound_ctrl:1
	v_pk_add_f32 v[236:237], v[236:237], v[240:241]
	s_nop 1
	v_mov_b32_dpp v241, v237 row_ror:4 row_mask:0xf bank_mask:0xf bound_ctrl:1
	v_mov_b32_dpp v240, v236 row_ror:4 row_mask:0xf bank_mask:0xf bound_ctrl:1
	v_pk_add_f32 v[236:237], v[236:237], v[240:241]
	s_nop 1
	v_mov_b32_dpp v241, v237 row_ror:8 row_mask:0xf bank_mask:0xf bound_ctrl:1
	v_mov_b32_dpp v240, v236 row_ror:8 row_mask:0xf bank_mask:0xf bound_ctrl:1
	v_pk_add_f32 v[236:237], v[236:237], v[240:241]
	s_nop 0
	v_pk_fma_f32 v[186:187], v[186:187], v[238:239], v[236:237]
	v_mov_b32_e32 v236, v239
	v_mov_b32_e32 v239, v160
	v_cvt_pk_bf16_f32 v160, v162, v165
	ds_write_b16 v223, v160 offset:240
	v_cvt_pk_bf16_f32 v160, v192, v165
	ds_write_b16 v224, v160 offset:272
	s_waitcnt lgkmcnt(0)
; __device__ __forceinline__ unsigned cvt_pk_bf16(float lo, float hi) { unsigned r; asm volatile("v_cvt_pk_bf16_f32 %0, %1, %2" : "=v"(r) : "v"(lo), "v"(hi)); return r; }
; __device__ __forceinline__ f32x4 mfma16(bf16x8 a, bf16x8 b, f32x4 c) { const f32x4 r = __builtin_amdgcn_mfma_f32_16x16x32_bf16(a, b, c, 0, 0, 0); asm volatile("" :: "v"(a), "v"(b)); return r; }
; __device__ __forceinline__ void attn_item(const Ptrs& P, unsigned char* lds, int b, int tq0, int tid) {
;     ...
; #pragma unroll
;             for (int dt = 0; dt < 16; ++dt) oacc[dt][j] *= scale;
;             Pw[(4 * g + j) * 40 + r16] = (bf16_t)(cvt_pk_bf16(p0, 0.f) & 0xffffu);
;             Pw[(4 * g + j) * 40 + 16 + r16] = (bf16_t)(cvt_pk_bf16(p1, 0.f) & 0xffffu);
;         }
;         asm volatile("s_waitcnt lgkmcnt(0)" ::: "memory");
;         const bf16x8 Ap = *(const bf16x8*)(Pw + r16 * 40 + 8 * g);
; #pragma unroll
;         for (int hh = 0; hh < 4; ++hh) {
;             s16x4 r[8];
;             if (hh == 0) TR8(r, 0); else if (hh == 1) TR8(r, 128); else if (hh == 2) TR8(r, 256); else TR8(r, 384);
; #pragma unroll
;             for (int dt = 0; dt < 4; ++dt) { bf16x8 Bv; Bv[0] = r[2 * dt][0]; Bv[1] = r[2 * dt][1]; Bv[2] = r[2 * dt][2]; Bv[3] = r[2 * dt][3];
;                 Bv[4] = r[2 * dt + 1][0]; Bv[5] = r[2 * dt + 1][1]; Bv[6] = r[2 * dt + 1][2]; Bv[7] = r[2 * dt + 1][3];
;                 oacc[4 * hh + dt] = mfma16(Ap, Bv, oacc[4 * hh + dt]); }
;         }
	v_mov_b32_e32 v237, v238
	v_mov_b32_e32 v238, v161
	ds_read_b128 v[160:163], v232
	v_pk_mul_f32 v[110:111], v[110:111], v[236:237]
	v_pk_mul_f32 v[108:109], v[108:109], v[238:239]
	v_pk_mul_f32 v[102:103], v[102:103], v[236:237]
	v_pk_mul_f32 v[100:101], v[100:101], v[238:239]
	v_pk_mul_f32 v[86:87], v[86:87], v[236:237]
	v_pk_mul_f32 v[84:85], v[84:85], v[238:239]
	v_pk_mul_f32 v[70:71], v[70:71], v[236:237]
	v_pk_mul_f32 v[68:69], v[68:69], v[238:239]
	v_pk_mul_f32 v[50:51], v[50:51], v[236:237]
	v_pk_mul_f32 v[48:49], v[48:49], v[238:239]
	v_pk_mul_f32 v[42:43], v[42:43], v[236:237]
	v_pk_mul_f32 v[40:41], v[40:41], v[238:239]
	v_pk_mul_f32 v[38:39], v[38:39], v[236:237]
	v_pk_mul_f32 v[36:37], v[36:37], v[238:239]
	v_pk_mul_f32 v[34:35], v[34:35], v[236:237]
	v_pk_mul_f32 v[32:33], v[32:33], v[238:239]
	v_pk_mul_f32 v[150:151], v[150:151], v[236:237]
	v_pk_mul_f32 v[148:149], v[148:149], v[238:239]
	v_pk_mul_f32 v[138:139], v[138:139], v[236:237]
	v_pk_mul_f32 v[136:137], v[136:137], v[238:239]
	v_pk_mul_f32 v[126:127], v[126:127], v[236:237]
	v_pk_mul_f32 v[124:125], v[124:125], v[238:239]
	v_pk_mul_f32 v[114:115], v[114:115], v[236:237]
	v_pk_mul_f32 v[112:113], v[112:113], v[238:239]
	v_pk_mul_f32 v[106:107], v[106:107], v[236:237]
	v_pk_mul_f32 v[104:105], v[104:105], v[238:239]
	v_pk_mul_f32 v[98:99], v[98:99], v[236:237]
	v_pk_mul_f32 v[96:97], v[96:97], v[238:239]
	v_pk_mul_f32 v[82:83], v[82:83], v[236:237]
	v_pk_mul_f32 v[80:81], v[80:81], v[238:239]
	v_pk_mul_f32 v[46:47], v[46:47], v[236:237]
	v_pk_mul_f32 v[44:45], v[44:45], v[238:239]
	ds_read_b64_tr_b16 v[236:237], v222 offset:0+0
	ds_read_b64_tr_b16 v[238:239], v222 offset:0+2112
	ds_read_b64_tr_b16 v[240:241], v222 offset:0+32
	ds_read_b64_tr_b16 v[242:243], v222 offset:0+2144
	ds_read_b64_tr_b16 v[244:245], v222 offset:0+64
	ds_read_b64_tr_b16 v[246:247], v222 offset:0+2176
	ds_read_b64_tr_b16 v[248:249], v222 offset:0+96
	ds_read_b64_tr_b16 v[250:251], v222 offset:0+2208
	s_waitcnt lgkmcnt(0)
	s_waitcnt lgkmcnt(0)
	v_mfma_f32_16x16x32_bf16 v[108:111], v[160:163], v[236:239], v[108:111]
	v_mfma_f32_16x16x32_bf16 v[100:103], v[160:163], v[240:243], v[100:103]
	v_mfma_f32_16x16x32_bf16 v[84:87], v[160:163], v[244:247], v[84:87]
	v_mfma_f32_16x16x32_bf16 v[68:71], v[160:163], v[248:251], v[68:71]
	ds_read_b64_tr_b16 v[236:237], v222 offset:128+0
	ds_read_b64_tr_b16 v[238:239], v222 offset:128+2112
	ds_read_b64_tr_b16 v[240:241], v222 offset:128+32
	ds_read_b64_tr_b16 v[242:243], v222 offset:128+2144
	ds_read_b64_tr_b16 v[244:245], v222 offset:128+64
	ds_read_b64_tr_b16 v[246:247], v222 offset:128+2176
	ds_read_b64_tr_b16 v[248:249], v222 offset:128+96
	ds_read_b64_tr_b16 v[250:251], v222 offset:128+2208
	s_waitcnt lgkmcnt(0)
	s_nop 0
	v_mfma_f32_16x16x32_bf16 v[48:51], v[160:163], v[236:239], v[48:51]
	v_mfma_f32_16x16x32_bf16 v[40:43], v[160:163], v[240:243], v[40:43]
	v_mfma_f32_16x16x32_bf16 v[36:39], v[160:163], v[244:247], v[36:39]
	v_mfma_f32_16x16x32_bf16 v[32:35], v[160:163], v[248:251], v[32:35]
	ds_read_b64_tr_b16 v[236:237], v222 offset:256+0
	ds_read_b64_tr_b16 v[238:239], v222 offset:256+2112
	ds_read_b64_tr_b16 v[240:241], v222 offset:256+32
	ds_read_b64_tr_b16 v[242:243], v222 offset:256+2144
	ds_read_b64_tr_b16 v[244:245], v222 offset:256+64
	ds_read_b64_tr_b16 v[246:247], v222 offset:256+2176
	ds_read_b64_tr_b16 v[248:249], v222 offset:256+96
	ds_read_b64_tr_b16 v[250:251], v222 offset:256+2208
	s_waitcnt lgkmcnt(0)
	s_nop 0
	v_mfma_f32_16x16x32_bf16 v[148:151], v[160:163], v[236:239], v[148:151]
	v_mfma_f32_16x16x32_bf16 v[136:139], v[160:163], v[240:243], v[136:139]
	v_mfma_f32_16x16x32_bf16 v[124:127], v[160:163], v[244:247], v[124:127]
	v_mfma_f32_16x16x32_bf16 v[112:115], v[160:163], v[248:251], v[112:115]
	ds_read_b64_tr_b16 v[236:237], v222 offset:384+0
	ds_read_b64_tr_b16 v[238:239], v222 offset:384+2112
	ds_read_b64_tr_b16 v[240:241], v222 offset:384+32
	ds_read_b64_tr_b16 v[242:243], v222 offset:384+2144
	ds_read_b64_tr_b16 v[244:245], v222 offset:384+64
	ds_read_b64_tr_b16 v[246:247], v222 offset:384+2176
	ds_read_b64_tr_b16 v[248:249], v222 offset:384+96
	ds_read_b64_tr_b16 v[250:251], v222 offset:384+2208
	s_waitcnt lgkmcnt(0)
	s_nop 0
	v_mfma_f32_16x16x32_bf16 v[104:107], v[160:163], v[236:239], v[104:107]
	v_mfma_f32_16x16x32_bf16 v[96:99], v[160:163], v[240:243], v[96:99]
	v_mfma_f32_16x16x32_bf16 v[80:83], v[160:163], v[244:247], v[80:83]
	v_mfma_f32_16x16x32_bf16 v[44:47], v[160:163], v[248:251], v[44:47]
	s_cbranch_scc1 .LBB0_928
	v_mov_b32_e32 v162, v235
	v_mov_b32_e32 v163, v234
	v_mov_b32_e32 v160, v233
	v_mov_b32_e32 v161, v164
	s_branch .LBB0_924

; __global__ void __launch_bounds__(512, 2) mega_fwd(Args args) {
;     extern __shared__ __attribute__((aligned(16))) unsigned char lds[];
	.amdhsa_kernel _Z8mega_fwd4Args
		.amdhsa_group_segment_fixed_size 12288
		.amdhsa_private_segment_fixed_size 0
		.amdhsa_kernarg_size 416
		.amdhsa_user_sgpr_count 2
		.amdhsa_user_sgpr_dispatch_ptr 0
		.amdhsa_user_sgpr_queue_ptr 0
		.amdhsa_user_sgpr_kernarg_segment_ptr 1
		.amdhsa_user_sgpr_dispatch_id 0
		.amdhsa_user_sgpr_kernarg_preload_length 0
		.amdhsa_user_sgpr_kernarg_preload_offset 0
		.amdhsa_user_sgpr_private_segment_size 0
		.amdhsa_uses_dynamic_stack 0
		.amdhsa_enable_private_segment 0
		.amdhsa_system_sgpr_workgroup_id_x 1
		.amdhsa_system_sgpr_workgroup_id_y 0
		.amdhsa_system_sgpr_workgroup_id_z 0
		.amdhsa_system_sgpr_workgroup_info 0
		.amdhsa_system_vgpr_workitem_id 2
		.amdhsa_next_free_vgpr 254
		.amdhsa_next_free_sgpr 98
		.amdhsa_accum_offset 256
		.amdhsa_reserve_vcc 1
		.amdhsa_float_round_mode_32 0
		.amdhsa_float_round_mode_16_64 0
		.amdhsa_float_denorm_mode_32 3
		.amdhsa_float_denorm_mode_16_64 3
		.amdhsa_dx10_clamp 1
		.amdhsa_ieee_mode 1
		.amdhsa_fp16_overflow 0
		.amdhsa_tg_split 0
		.amdhsa_exception_fp_ieee_invalid_op 0
		.amdhsa_exception_fp_denorm_src 0
		.amdhsa_exception_fp_ieee_div_zero 0
		.amdhsa_exception_fp_ieee_overflow 0
		.amdhsa_exception_fp_ieee_underflow 0
		.amdhsa_exception_fp_ieee_inexact 0
		.amdhsa_exception_int_div_zero 0
	.end_amdhsa_kernel

; __global__ void __launch_bounds__(512, 2) mega_fwd(Args args) {
;     extern __shared__ __attribute__((aligned(16))) unsigned char lds[];
amdhsa.kernels:
  - .agpr_count:     0
    .args:
      - .offset:         0
        .size:           160
        .value_kind:     by_value
      - .offset:         160
        .size:           4
        .value_kind:     hidden_block_count_x
      - .offset:         164
        .size:           4
        .value_kind:     hidden_block_count_y
      - .offset:         168
        .size:           4
        .value_kind:     hidden_block_count_z
      - .offset:         172
        .size:           2
        .value_kind:     hidden_group_size_x
      - .offset:         174
        .size:           2
        .value_kind:     hidden_group_size_y
      - .offset:         176
        .size:           2
        .value_kind:     hidden_group_size_z
      - .offset:         178
        .size:           2
        .value_kind:     hidden_remainder_x
      - .offset:         180
        .size:           2
        .value_kind:     hidden_remainder_y
      - .offset:         182
        .size:           2
        .value_kind:     hidden_remainder_z
      - .offset:         200
        .size:           8
        .value_kind:     hidden_global_offset_x
      - .offset:         208
        .size:           8
        .value_kind:     hidden_global_offset_y
      - .offset:         216
        .size:           8
        .value_kind:     hidden_global_offset_z
      - .offset:         224
        .size:           2
        .value_kind:     hidden_grid_dims
      - .offset:         248
        .size:           8
        .value_kind:     hidden_multigrid_sync_arg
      - .offset:         280
        .size:           4
        .value_kind:     hidden_dynamic_lds_size
    .group_segment_fixed_size: 12288
    .kernarg_segment_align: 8
    .kernarg_segment_size: 416
    .language:       OpenCL C
    .language_version:
      - 2
      - 0
    .max_flat_workgroup_size: 512
    .name:           _Z8mega_fwd4Args
    .private_segment_fixed_size: 0
    .sgpr_count:     104
    .sgpr_spill_count: 20
    .symbol:         _Z8mega_fwd4Args.kd
    .uniform_work_group_size: 1
    .uses_dynamic_stack: false
    .vgpr_count:     254
    .vgpr_spill_count: 0
    .wavefront_size: 64
